# GEMM unit prologues: zero-fill MFMAs issued at the unit-loop header so they run under the scalar unit-index arithmetic (its VGPR temps renamed off the accumulators)
# baseline (speedup 1.0000x reference)
.LBB0_118:
	v_mov_b32_e32 v2, 0
	v_mov_b32_e32 v3, 0
	v_mov_b32_e32 v4, 0
	v_mov_b32_e32 v5, 0
	v_mov_b32_e32 v6, 0
	v_mov_b32_e32 v7, 0
	v_mov_b32_e32 v8, 0
	v_mov_b32_e32 v9, 0
	v_mov_b32_e32 v10, 0
	v_mov_b32_e32 v11, 0
	v_mov_b32_e32 v12, 0
	v_mov_b32_e32 v13, 0
	v_mov_b32_e32 v14, 0
	v_mov_b32_e32 v15, 0
	v_mov_b32_e32 v16, 0
	v_mov_b32_e32 v17, 0
	v_mfma_f32_32x32x16_bf16 v[18:33], v[2:5], v[2:5], 0
	v_mfma_f32_32x32x16_bf16 v[34:49], v[2:5], v[2:5], 0
	v_mfma_f32_32x32x16_bf16 v[50:65], v[2:5], v[2:5], 0
	v_mfma_f32_32x32x16_bf16 v[66:81], v[2:5], v[2:5], 0
	v_mfma_f32_32x32x16_bf16 v[82:97], v[2:5], v[2:5], 0
	v_mfma_f32_32x32x16_bf16 v[98:113], v[2:5], v[2:5], 0
	v_mfma_f32_32x32x16_bf16 v[114:129], v[2:5], v[2:5], 0
	s_add_i32 s38, s38, 1
	s_mul_i32 s0, s38, s73
	s_mul_hi_u32 s1, s38, s83
	s_add_i32 s1, s1, s0
	s_mul_i32 s0, s38, s83
	s_add_u32 s0, s0, s92
	s_addc_u32 s1, s1, s72
	v_mov_b64_e32 v[200:201], 0xf00
	v_cmp_lt_i64_e64 s[2:3], s[0:1], v[200:201]
	v_mov_b64_e32 v[200:201], 0xeff
	v_cmp_gt_i64_e32 vcc, s[0:1], v[200:201]
	s_cbranch_vccnz .LBB0_120
	s_ashr_i32 s1, s0, 31
	s_lshr_b32 s1, s1, 29
	s_add_i32 s1, s0, s1
	s_ashr_i32 s18, s1, 3
	s_and_b32 s1, s1, -8
	s_sub_i32 s0, s0, s1
	s_cmp_lt_i32 s0, 0
	s_cselect_b32 s1, s85, 0x1e0
	s_mul_i32 s0, s0, s1
	s_add_i32 s0, s0, s18
	s_mul_hi_i32 s1, s0, 0x88888889
	s_add_i32 s1, s1, s0
	s_lshr_b32 s18, s1, 31
	s_ashr_i32 s1, s1, 6
	s_add_i32 s1, s1, s18
	s_lshl_b32 s18, s1, 3
	s_sub_i32 s19, 0x100, s18
	s_min_i32 s19, s19, 8
	s_abs_i32 s39, s19
	v_cvt_f32_u32_e32 v200, s39
	s_sub_i32 s43, 0, s39
	s_mulk_i32 s1, 0x78
	s_sub_i32 s0, s0, s1
	v_rcp_iflag_f32_e32 v200, v200
	s_abs_i32 s1, s0
	s_xor_b32 s40, s0, s19
	s_ashr_i32 s40, s40, 31
	v_mul_f32_e32 v200, 0x4f7ffffe, v200
	v_cvt_u32_f32_e32 v200, v200
	s_nop 0
	v_readfirstlane_b32 s44, v200
	s_mul_i32 s43, s43, s44
	s_mul_hi_u32 s43, s44, s43
	s_add_i32 s44, s44, s43
	s_mul_hi_u32 s43, s1, s44
	s_mul_i32 s44, s43, s39
	s_sub_i32 s1, s1, s44
	s_add_i32 s45, s43, 1
	s_sub_i32 s44, s1, s39
	s_cmp_ge_u32 s1, s39
	s_cselect_b32 s43, s45, s43
	s_cselect_b32 s1, s44, s1
	s_add_i32 s44, s43, 1
	s_cmp_ge_u32 s1, s39
	s_cselect_b32 s1, s44, s43
	s_xor_b32 s1, s1, s40
	s_sub_i32 s39, s1, s40
	s_mul_i32 s1, s39, s19
	s_sub_i32 s0, s0, s1
	s_add_i32 s40, s18, s0
.LBB0_120:
	v_cndmask_b32_e64 v200, 0, 1, s[2:3]
	v_cmp_ne_u32_e64 s[0:1], 1, v200
	s_andn2_b64 vcc, exec, s[2:3]
	s_mov_b64 s[2:3], s[20:21]
	s_cbranch_vccnz .LBB0_122
	s_ashr_i32 s2, s40, 31
	s_mul_hi_u32 s3, s8, s40
	s_mul_i32 s2, s8, s2
	s_add_i32 s2, s3, s2
	s_mul_i32 s3, s9, s40
	s_add_i32 s3, s2, s3
	s_mul_i32 s2, s8, s40
	s_add_u32 s2, s4, s2
	s_addc_u32 s3, s5, s3

.LBB0_124:
	s_andn2_b64 vcc, exec, s[14:15]
	s_waitcnt vmcnt(0)
	s_nop 15
	s_nop 3
	s_cbranch_vccnz .LBB0_127
	s_add_u32 s20, s20, 0x80
	s_addc_u32 s21, s21, 0
	s_add_u32 s43, s22, 0x100
	s_addc_u32 s44, s23, 0
	s_mov_b32 s22, 0
	s_mov_b64 s[50:51], 0x80

.LBB0_420:
	v_mov_b32_e32 v2, 0
	v_mov_b32_e32 v3, 0
	v_mov_b32_e32 v4, 0
	v_mov_b32_e32 v5, 0
	v_mov_b32_e32 v6, 0
	v_mov_b32_e32 v7, 0
	v_mov_b32_e32 v8, 0
	v_mov_b32_e32 v9, 0
	v_mov_b32_e32 v10, 0
	v_mov_b32_e32 v11, 0
	v_mov_b32_e32 v12, 0
	v_mov_b32_e32 v13, 0
	v_mov_b32_e32 v14, 0
	v_mov_b32_e32 v15, 0
	v_mov_b32_e32 v16, 0
	v_mov_b32_e32 v17, 0
	v_mfma_f32_32x32x16_bf16 v[18:33], v[2:5], v[2:5], 0
	v_mfma_f32_32x32x16_bf16 v[34:49], v[2:5], v[2:5], 0
	v_mfma_f32_32x32x16_bf16 v[50:65], v[2:5], v[2:5], 0
	v_mfma_f32_32x32x16_bf16 v[66:81], v[2:5], v[2:5], 0
	v_mfma_f32_32x32x16_bf16 v[82:97], v[2:5], v[2:5], 0
	v_mfma_f32_32x32x16_bf16 v[98:113], v[2:5], v[2:5], 0
	v_mfma_f32_32x32x16_bf16 v[114:129], v[2:5], v[2:5], 0
	s_add_i32 s47, s47, 1
	s_mul_i32 s0, s47, s73
	s_mul_hi_u32 s1, s47, s83
	s_add_i32 s1, s1, s0
	s_mul_i32 s0, s47, s83
	s_add_u32 s6, s0, s92
	s_addc_u32 s7, s1, s72
	v_mov_b64_e32 v[200:201], 0x300
	v_cmp_lt_i64_e64 s[0:1], s[6:7], v[200:201]
	v_mov_b64_e32 v[200:201], 0x2ff
	v_cmp_gt_i64_e32 vcc, s[6:7], v[200:201]
	s_cbranch_vccnz .LBB0_422
	s_ashr_i32 s7, s6, 31
	s_lshr_b32 s7, s7, 29
	s_add_i32 s7, s6, s7
	s_ashr_i32 s22, s7, 3
	s_and_b32 s7, s7, -8
	s_sub_i32 s6, s6, s7
	s_cmp_lt_i32 s6, 0
	s_cselect_b32 s7, s56, 0x60
	s_mul_i32 s6, s6, s7
	s_add_i32 s6, s6, s22
	s_mul_hi_i32 s7, s6, 0x2aaaaaab
	s_lshr_b32 s22, s7, 31
	s_ashr_i32 s7, s7, 2
	s_add_i32 s7, s7, s22
	s_lshl_b32 s22, s7, 3
	s_sub_i32 s23, 0x100, s22
	s_min_i32 s23, s23, 8
	s_abs_i32 s24, s23
	v_cvt_f32_u32_e32 v200, s24
	s_sub_i32 s48, 0, s24
	s_mul_i32 s7, s7, 24
	s_sub_i32 s6, s6, s7
	v_rcp_iflag_f32_e32 v200, v200
	s_abs_i32 s7, s6
	s_xor_b32 s25, s6, s23
	s_ashr_i32 s25, s25, 31
	v_mul_f32_e32 v200, 0x4f7ffffe, v200
	v_cvt_u32_f32_e32 v200, v200
	s_nop 0
	v_readfirstlane_b32 s49, v200
	s_mul_i32 s48, s48, s49
	s_mul_hi_u32 s48, s49, s48
	s_add_i32 s49, s49, s48
	s_mul_hi_u32 s48, s7, s49
	s_mul_i32 s49, s48, s24
	s_sub_i32 s7, s7, s49
	s_add_i32 s51, s48, 1
	s_sub_i32 s49, s7, s24
	s_cmp_ge_u32 s7, s24
	s_cselect_b32 s48, s51, s48
	s_cselect_b32 s7, s49, s7
	s_add_i32 s49, s48, 1
	s_cmp_ge_u32 s7, s24
	s_cselect_b32 s7, s49, s48
	s_xor_b32 s7, s7, s25
	s_sub_i32 s48, s7, s25
	s_mul_i32 s7, s48, s23
	s_sub_i32 s6, s6, s7
	s_add_i32 s49, s22, s6
.LBB0_422:
	v_cndmask_b32_e64 v200, 0, 1, s[0:1]
	v_cmp_ne_u32_e64 s[6:7], 1, v200
	s_andn2_b64 vcc, exec, s[0:1]
	s_mov_b64 s[22:23], s[28:29]
	s_cbranch_vccnz .LBB0_424
	s_ashr_i32 s0, s49, 31
	s_mul_hi_u32 s1, s8, s49
	s_mul_i32 s0, s8, s0
	s_add_i32 s0, s1, s0
	s_mul_i32 s1, s9, s49
	s_add_i32 s0, s0, s1
	s_mul_i32 s1, s8, s49
	s_add_u32 s22, s2, s1
	s_addc_u32 s23, s3, s0

.LBB0_426:
	s_andn2_b64 vcc, exec, s[18:19]
	s_nop 15
	s_nop 3
	s_cbranch_vccnz .LBB0_430
	s_add_u32 s0, s28, 0x80
	s_addc_u32 s1, s29, 0
	s_add_u32 s28, s26, 0x100
	s_addc_u32 s29, s27, 0
	s_mov_b32 s26, 0
	s_mov_b64 s[64:65], 0x80

.LBB0_442:
	v_mov_b32_e32 v2, 0
	v_mov_b32_e32 v3, 0
	v_mov_b32_e32 v4, 0
	v_mov_b32_e32 v5, 0
	v_mov_b32_e32 v6, 0
	v_mov_b32_e32 v7, 0
	v_mov_b32_e32 v8, 0
	v_mov_b32_e32 v9, 0
	v_mov_b32_e32 v10, 0
	v_mov_b32_e32 v11, 0
	v_mov_b32_e32 v12, 0
	v_mov_b32_e32 v13, 0
	v_mov_b32_e32 v14, 0
	v_mov_b32_e32 v15, 0
	v_mov_b32_e32 v16, 0
	v_mov_b32_e32 v17, 0
	v_mfma_f32_32x32x16_bf16 v[18:33], v[2:5], v[2:5], 0
	v_mfma_f32_32x32x16_bf16 v[34:49], v[2:5], v[2:5], 0
	v_mfma_f32_32x32x16_bf16 v[50:65], v[2:5], v[2:5], 0
	v_mfma_f32_32x32x16_bf16 v[66:81], v[2:5], v[2:5], 0
	v_mfma_f32_32x32x16_bf16 v[82:97], v[2:5], v[2:5], 0
	v_mfma_f32_32x32x16_bf16 v[98:113], v[2:5], v[2:5], 0
	v_mfma_f32_32x32x16_bf16 v[114:129], v[2:5], v[2:5], 0
	s_add_i32 s38, s38, 1
	s_mul_i32 s0, s38, s73
	s_mul_hi_u32 s1, s38, s83
	s_add_i32 s1, s1, s0
	s_mul_i32 s0, s38, s83
	s_add_u32 s0, s0, s92
	s_addc_u32 s1, s1, s72
	v_cmp_gt_i64_e32 vcc, s[0:1], v[240:241]
	v_cmp_lt_i64_e64 s[2:3], s[0:1], v[238:239]
	s_cbranch_vccnz .LBB0_448
	s_ashr_i32 s1, s0, 31
	s_lshr_b32 s1, s1, 29
	s_add_i32 s16, s0, s1
	s_and_b32 s1, s16, -8
	s_sub_i32 s17, s0, s1
	s_cmp_gt_i32 s17, -1
	s_mov_b64 s[0:1], -1
	s_cbranch_scc0 .LBB0_445
	s_lshl_b32 s39, s17, 7
	s_mov_b64 s[0:1], 0

.LBB0_447:
	s_ashr_i32 s0, s16, 3
	s_add_i32 s0, s39, s0
	s_ashr_i32 s1, s0, 31
	s_lshr_b32 s1, s1, 27
	s_add_i32 s1, s0, s1
	s_ashr_i32 s16, s1, 5
	s_lshl_b32 s16, s16, 3
	s_sub_i32 s17, 0x100, s16
	s_min_i32 s17, s17, 8
	s_abs_i32 s39, s17
	v_cvt_f32_u32_e32 v200, s39
	s_sub_i32 s43, 0, s39
	s_andn2_b32 s1, s1, 31
	s_sub_i32 s0, s0, s1
	v_rcp_iflag_f32_e32 v200, v200
	s_abs_i32 s1, s0
	s_xor_b32 s40, s0, s17
	s_ashr_i32 s40, s40, 31
	v_mul_f32_e32 v200, 0x4f7ffffe, v200
	v_cvt_u32_f32_e32 v200, v200
	s_nop 0
	v_readfirstlane_b32 s44, v200
	s_mul_i32 s43, s43, s44
	s_mul_hi_u32 s43, s44, s43
	s_add_i32 s44, s44, s43
	s_mul_hi_u32 s43, s1, s44
	s_mul_i32 s44, s43, s39
	s_sub_i32 s1, s1, s44
	s_add_i32 s45, s43, 1
	s_sub_i32 s44, s1, s39
	s_cmp_ge_u32 s1, s39
	s_cselect_b32 s43, s45, s43
	s_cselect_b32 s1, s44, s1
	s_add_i32 s44, s43, 1
	s_cmp_ge_u32 s1, s39
	s_cselect_b32 s1, s44, s43
	s_xor_b32 s1, s1, s40
	s_sub_i32 s39, s1, s40
	s_mul_i32 s1, s39, s17
	s_sub_i32 s0, s0, s1
	s_add_i32 s40, s16, s0
.LBB0_448:
	s_nop 0
	v_cndmask_b32_e64 v200, 0, 1, s[2:3]
	v_cmp_ne_u32_e64 s[0:1], 1, v200
	s_andn2_b64 vcc, exec, s[2:3]
	s_mov_b64 s[2:3], s[18:19]
	s_cbranch_vccnz .LBB0_450
	s_ashr_i32 s2, s40, 31
	s_mul_hi_u32 s3, s6, s40
	s_mul_i32 s2, s6, s2
	s_add_i32 s2, s3, s2
	s_mul_i32 s3, s7, s40
	s_add_i32 s3, s2, s3
	s_mul_i32 s2, s6, s40
	s_add_u32 s2, s22, s2
	s_addc_u32 s3, s23, s3

.LBB0_452:
	s_andn2_b64 vcc, exec, s[12:13]
	s_nop 15
	s_nop 3
	s_cbranch_vccnz .LBB0_455
	s_add_u32 s18, s18, 0x80
	s_addc_u32 s19, s19, 0
	s_add_u32 s43, s20, 0x100
	s_addc_u32 s44, s21, 0
	s_mov_b32 s20, 0
	s_mov_b64 s[50:51], 0x80

.LBB0_599:
	v_mov_b32_e32 v2, 0
	v_mov_b32_e32 v3, 0
	v_mov_b32_e32 v4, 0
	v_mov_b32_e32 v5, 0
	v_mov_b32_e32 v6, 0
	v_mov_b32_e32 v7, 0
	v_mov_b32_e32 v8, 0
	v_mov_b32_e32 v9, 0
	v_mov_b32_e32 v10, 0
	v_mov_b32_e32 v11, 0
	v_mov_b32_e32 v12, 0
	v_mov_b32_e32 v13, 0
	v_mov_b32_e32 v14, 0
	v_mov_b32_e32 v15, 0
	v_mov_b32_e32 v16, 0
	v_mov_b32_e32 v17, 0
	v_mfma_f32_32x32x16_bf16 v[18:33], v[2:5], v[2:5], 0
	v_mfma_f32_32x32x16_bf16 v[34:49], v[2:5], v[2:5], 0
	v_mfma_f32_32x32x16_bf16 v[50:65], v[2:5], v[2:5], 0
	v_mfma_f32_32x32x16_bf16 v[66:81], v[2:5], v[2:5], 0
	v_mfma_f32_32x32x16_bf16 v[82:97], v[2:5], v[2:5], 0
	v_mfma_f32_32x32x16_bf16 v[98:113], v[2:5], v[2:5], 0
	v_mfma_f32_32x32x16_bf16 v[114:129], v[2:5], v[2:5], 0
	s_add_i32 s40, s40, 1
	s_mul_i32 s0, s40, s73
	s_mul_hi_u32 s1, s40, s83
	s_add_i32 s1, s1, s0
	s_mul_i32 s0, s40, s83
	s_add_u32 s0, s0, s92
	s_addc_u32 s1, s1, s72
	v_cmp_gt_i64_e32 vcc, s[0:1], v[240:241]
	v_cmp_lt_i64_e64 s[2:3], s[0:1], v[238:239]
	s_cbranch_vccnz .LBB0_605
	s_ashr_i32 s1, s0, 31
	s_lshr_b32 s1, s1, 29
	s_add_i32 s18, s0, s1
	s_and_b32 s1, s18, -8
	s_sub_i32 s19, s0, s1
	s_cmp_gt_i32 s19, -1
	s_mov_b64 s[0:1], -1
	s_cbranch_scc0 .LBB0_602
	s_lshl_b32 s41, s19, 7
	s_mov_b64 s[0:1], 0

.LBB0_604:
	s_ashr_i32 s0, s18, 3
	s_add_i32 s0, s41, s0
	s_ashr_i32 s1, s0, 31
	s_lshr_b32 s1, s1, 27
	s_add_i32 s1, s0, s1
	s_ashr_i32 s18, s1, 5
	s_lshl_b32 s18, s18, 3
	s_sub_i32 s19, 0x100, s18
	s_min_i32 s19, s19, 8
	s_abs_i32 s41, s19
	v_cvt_f32_u32_e32 v200, s41
	s_sub_i32 s45, 0, s41
	s_andn2_b32 s1, s1, 31
	s_sub_i32 s0, s0, s1
	v_rcp_iflag_f32_e32 v200, v200
	s_abs_i32 s1, s0
	s_xor_b32 s42, s0, s19
	s_ashr_i32 s42, s42, 31
	v_mul_f32_e32 v200, 0x4f7ffffe, v200
	v_cvt_u32_f32_e32 v200, v200
	s_nop 0
	v_readfirstlane_b32 s46, v200
	s_mul_i32 s45, s45, s46
	s_mul_hi_u32 s45, s46, s45
	s_add_i32 s46, s46, s45
	s_mul_hi_u32 s45, s1, s46
	s_mul_i32 s46, s45, s41
	s_sub_i32 s1, s1, s46
	s_add_i32 s47, s45, 1
	s_sub_i32 s46, s1, s41
	s_cmp_ge_u32 s1, s41
	s_cselect_b32 s45, s47, s45
	s_cselect_b32 s1, s46, s1
	s_add_i32 s46, s45, 1
	s_cmp_ge_u32 s1, s41
	s_cselect_b32 s1, s46, s45
	s_xor_b32 s1, s1, s42
	s_sub_i32 s41, s1, s42
	s_mul_i32 s1, s41, s19
	s_sub_i32 s0, s0, s1
	s_add_i32 s42, s18, s0
.LBB0_605:
	s_nop 0
	v_cndmask_b32_e64 v200, 0, 1, s[2:3]
	v_cmp_ne_u32_e64 s[0:1], 1, v200
	s_andn2_b64 vcc, exec, s[2:3]
	s_mov_b64 s[2:3], s[20:21]
	s_cbranch_vccnz .LBB0_607
	s_ashr_i32 s2, s42, 31
	s_mul_hi_u32 s3, s8, s42
	s_mul_i32 s2, s8, s2
	s_add_i32 s2, s3, s2
	s_mul_i32 s3, s9, s42
	s_add_i32 s3, s2, s3
	s_mul_i32 s2, s8, s42
	s_add_u32 s2, s24, s2
	s_addc_u32 s3, s25, s3

.LBB0_609:
	s_andn2_b64 vcc, exec, s[14:15]
	s_waitcnt vmcnt(0)
	s_nop 15
	s_nop 3
	s_cbranch_vccnz .LBB0_612
	s_add_u32 s20, s20, 0x80
	s_addc_u32 s21, s21, 0
	s_add_u32 s45, s22, 0x100
	s_addc_u32 s46, s23, 0
	s_mov_b32 s22, 0
	s_mov_b64 s[52:53], 0x80

.LBB0_731:
	v_mov_b32_e32 v2, 0
	v_mov_b32_e32 v3, 0
	v_mov_b32_e32 v4, 0
	v_mov_b32_e32 v5, 0
	v_mov_b32_e32 v6, 0
	v_mov_b32_e32 v7, 0
	v_mov_b32_e32 v8, 0
	v_mov_b32_e32 v9, 0
	v_mov_b32_e32 v10, 0
	v_mov_b32_e32 v11, 0
	v_mov_b32_e32 v12, 0
	v_mov_b32_e32 v13, 0
	v_mov_b32_e32 v14, 0
	v_mov_b32_e32 v15, 0
	v_mov_b32_e32 v16, 0
	v_mov_b32_e32 v17, 0
	v_mfma_f32_32x32x16_bf16 v[18:33], v[2:5], v[2:5], 0
	v_mfma_f32_32x32x16_bf16 v[34:49], v[2:5], v[2:5], 0
	v_mfma_f32_32x32x16_bf16 v[50:65], v[2:5], v[2:5], 0
	v_mfma_f32_32x32x16_bf16 v[66:81], v[2:5], v[2:5], 0
	v_mfma_f32_32x32x16_bf16 v[82:97], v[2:5], v[2:5], 0
	v_mfma_f32_32x32x16_bf16 v[98:113], v[2:5], v[2:5], 0
	v_mfma_f32_32x32x16_bf16 v[114:129], v[2:5], v[2:5], 0
	s_add_i32 s63, s63, 1
	s_mul_i32 s0, s63, s73
	s_mul_hi_u32 s1, s63, s83
	s_add_i32 s1, s1, s0
	s_mul_i32 s0, s63, s83
	s_add_u32 s0, s0, s92
	s_addc_u32 s1, s1, s72
	v_mov_b64_e32 v[200:201], 0x1600
	v_cmp_lt_i64_e64 s[2:3], s[0:1], v[200:201]
	v_mov_b64_e32 v[200:201], 0x15ff
	v_cmp_gt_i64_e32 vcc, s[0:1], v[200:201]
	s_cbranch_vccnz .LBB0_733
	s_ashr_i32 s1, s0, 31
	s_lshr_b32 s1, s1, 29
	s_add_i32 s1, s0, s1
	s_ashr_i32 s40, s1, 3
	s_and_b32 s1, s1, -8
	s_sub_i32 s0, s0, s1
	s_cmp_lt_i32 s0, 0
	s_cselect_b32 s1, s86, 0x2c0
	s_mul_i32 s0, s0, s1
	s_add_i32 s0, s0, s40
	s_mul_hi_i32 s1, s0, 0x2e8ba2e9
	s_lshr_b32 s40, s1, 31
	s_ashr_i32 s1, s1, 5
	s_add_i32 s1, s1, s40
	s_lshl_b32 s40, s1, 3
	s_sub_i32 s41, 0x100, s40
	s_min_i32 s41, s41, 8
	s_abs_i32 s42, s41
	v_cvt_f32_u32_e32 v200, s42
	s_sub_i32 s64, 0, s42
	s_mulk_i32 s1, 0xb0
	s_sub_i32 s0, s0, s1
	v_rcp_iflag_f32_e32 v200, v200
	s_abs_i32 s1, s0
	s_xor_b32 s43, s0, s41
	s_ashr_i32 s43, s43, 31
	v_mul_f32_e32 v200, 0x4f7ffffe, v200
	v_cvt_u32_f32_e32 v200, v200
	s_nop 0
	v_readfirstlane_b32 s65, v200
	s_mul_i32 s64, s64, s65
	s_mul_hi_u32 s64, s65, s64
	s_add_i32 s65, s65, s64
	s_mul_hi_u32 s64, s1, s65
	s_mul_i32 s65, s64, s42
	s_sub_i32 s1, s1, s65
	s_add_i32 s67, s64, 1
	s_sub_i32 s65, s1, s42
	s_cmp_ge_u32 s1, s42
	s_cselect_b32 s64, s67, s64
	s_cselect_b32 s1, s65, s1
	s_add_i32 s65, s64, 1
	s_cmp_ge_u32 s1, s42
	s_cselect_b32 s1, s65, s64
	s_xor_b32 s1, s1, s43
	s_sub_i32 s64, s1, s43
	s_mul_i32 s1, s64, s41
	s_sub_i32 s0, s0, s1
	s_add_i32 s65, s40, s0
.LBB0_733:
	v_cndmask_b32_e64 v200, 0, 1, s[2:3]
	v_cmp_ne_u32_e64 s[0:1], 1, v200
	s_andn2_b64 vcc, exec, s[2:3]
	s_mov_b64 s[40:41], s[46:47]
	s_cbranch_vccnz .LBB0_735
	s_ashr_i32 s2, s65, 31
	s_mul_hi_u32 s3, s8, s65
	s_mul_i32 s2, s8, s2
	s_add_i32 s2, s3, s2
	s_mul_i32 s3, s9, s65
	s_add_i32 s2, s2, s3
	s_mul_i32 s3, s8, s65
	s_add_u32 s40, s4, s3
	s_addc_u32 s41, s5, s2

.LBB0_737:
	s_andn2_b64 vcc, exec, s[20:21]
	s_waitcnt vmcnt(0)
	s_nop 15
	s_nop 3
	s_cbranch_vccnz .LBB0_741
	s_add_u32 s2, s46, 0x80
	s_addc_u32 s3, s47, 0
	s_add_u32 s46, s44, 0x100
	s_addc_u32 s47, s45, 0
	s_mov_b32 s44, 0
	s_mov_b64 vcc, 0x80

.LBB0_882:
	s_ashr_i32 s0, s16, 3
	s_add_i32 s0, s39, s0
	s_ashr_i32 s1, s0, 31
	s_lshr_b32 s1, s1, 27
	s_add_i32 s1, s0, s1
	s_ashr_i32 s16, s1, 5
	s_lshl_b32 s16, s16, 3
	s_sub_i32 s17, 0x100, s16
	s_min_i32 s17, s17, 8
	s_abs_i32 s39, s17
	v_cvt_f32_u32_e32 v200, s39
	s_sub_i32 s43, 0, s39
	s_andn2_b32 s1, s1, 31
	s_sub_i32 s0, s0, s1
	v_rcp_iflag_f32_e32 v200, v200
	s_abs_i32 s1, s0
	s_xor_b32 s40, s0, s17
	s_ashr_i32 s40, s40, 31
	v_mul_f32_e32 v200, 0x4f7ffffe, v200
	v_cvt_u32_f32_e32 v200, v200
	s_nop 0
	v_readfirstlane_b32 s44, v200
	s_mul_i32 s43, s43, s44
	s_mul_hi_u32 s43, s44, s43
	s_add_i32 s44, s44, s43
	s_mul_hi_u32 s43, s1, s44
	s_mul_i32 s44, s43, s39
	s_sub_i32 s1, s1, s44
	s_add_i32 s45, s43, 1
	s_sub_i32 s44, s1, s39
	s_cmp_ge_u32 s1, s39
	s_cselect_b32 s43, s45, s43
	s_cselect_b32 s1, s44, s1
	s_add_i32 s44, s43, 1
	s_cmp_ge_u32 s1, s39
	s_cselect_b32 s1, s44, s43
	s_xor_b32 s1, s1, s40
	s_sub_i32 s39, s1, s40
	s_mul_i32 s1, s39, s17
	s_sub_i32 s0, s0, s1
	s_add_i32 s0, s0, s16
	s_sub_i32 s40, 0xff, s0
.LBB0_883:
	s_nop 0
	v_cndmask_b32_e64 v200, 0, 1, s[2:3]
	v_cmp_ne_u32_e64 s[0:1], 1, v200
	s_andn2_b64 vcc, exec, s[2:3]
	s_mov_b64 s[2:3], s[18:19]
	s_cbranch_vccnz .LBB0_885
	s_ashr_i32 s2, s40, 31
	s_mul_hi_u32 s3, s8, s40
	s_mul_i32 s2, s8, s2
	s_add_i32 s2, s3, s2
	s_mul_i32 s3, s9, s40
	s_add_i32 s3, s2, s3
	s_mul_i32 s2, s8, s40
	s_add_u32 s2, s22, s2
	s_addc_u32 s3, s23, s3

.LBB0_887:
	s_andn2_b64 vcc, exec, s[12:13]
	s_waitcnt vmcnt(0)
	s_nop 15
	s_nop 3
	s_cbranch_vccnz .LBB0_890
	s_add_u32 s18, s18, 0x80
	s_addc_u32 s19, s19, 0
	s_add_u32 s43, s20, 0x100
	s_addc_u32 s44, s21, 0
	s_mov_b32 s20, 0
	s_mov_b64 s[50:51], 0x80
